# layer-0 output-projection epilogue: f32 residual rows requested three row groups ahead instead of load-wait per group
# baseline (speedup 1.0000x reference)
; DI unsigned cvt_pk_bf16(float lo, float hi) { unsigned r; asm volatile("v_cvt_pk_bf16_f32 %0, %1, %2" : "=v"(r) : "v"(lo), "v"(hi)); return r; }
; DI float bf_lo(unsigned w) { return __uint_as_float(w << 16); }
; DI float bf_hi(unsigned w) { return __uint_as_float(w & 0xffff0000u); }
;   DI void fused(f32x4 (&acc)[2][2][4][2], const Unit& u, int wr, int wc, int, int, LAS unsigned char* lds, int tid_) const {
;     ...
; #pragma unroll
;     for (int ai = 0; ai < 2; ++ai) {
; #pragma unroll
;       for (int m = 0; m < 4; ++m) { const int rl = ai * HALF + m * 16 + rl0; const float r1 = rs[rl]; float ss = 0.f;
; #pragma unroll
;         for (int bj = 0; bj < 2; ++bj) { const size_t o = (size_t)(u.pm * BM + rl) * 2048 + col0 + bj * HALF;
;           f32x4 xa, xc;
;           if constexpr (XF32) { xa = *(const f32x4*)(xin32 + o); xc = *(const f32x4*)(xin32 + o + 4); }
;           else { const u32x4 w = xw[ai][m][bj]; xa = (f32x4){bf_lo(w.x), bf_hi(w.x), bf_lo(w.y), bf_hi(w.y)}; xc = (f32x4){bf_lo(w.z), bf_hi(w.z), bf_lo(w.w), bf_hi(w.w)}; }
;           const f32x4 t0 = xa + acc[ai][bj][m][0] * r1 * g0[bj], t1 = xc + acc[ai][bj][m][1] * r1 * g1[bj];
;           ss += t0[0] * t0[0] + t0[1] * t0[1] + t0[2] * t0[2] + t0[3] * t0[3] + t1[0] * t1[0] + t1[1] * t1[1] + t1[2] * t1[2] + t1[3] * t1[3];
;           if (xout32) { *(f32x4*)(xout32 + o) = t0; *(f32x4*)(xout32 + o + 4) = t1; }
;           else { u32x4 w; w.x = cvt_pk_bf16(t0[0], t0[1]); w.y = cvt_pk_bf16(t0[2], t0[3]); w.z = cvt_pk_bf16(t1[0], t1[1]); w.w = cvt_pk_bf16(t1[2], t1[3]); *(u32x4*)(xb + o) = w; } }
;         if (!xout32) { ss += __shfl_xor(ss, 16); ss += __shfl_xor(ss, 32); if (fq == 0) part[wc * 256 + rl] = ss; } }
.LBB0_684:
	s_or_b64 exec, exec, s[22:23]
	v_add_u32_e32 v148, s1, v157
	v_ashrrev_i32_e32 v149, 31, v148
	v_lshlrev_b64 v[158:159], 11, v[148:149]
	v_readlane_b32 s52, v254, 10
	v_lshl_add_u64 v[166:167], v[158:159], 0, v[146:147]
	v_readlane_b32 s53, v254, 11
	v_lshl_add_u32 v156, v157, 2, 0
	s_waitcnt lgkmcnt(0)
	v_lshl_add_u64 v[168:169], v[166:167], 2, s[52:53]
	v_mov_b32_e32 v224, v168
	v_mov_b32_e32 v225, v169
	global_load_dwordx4 v[170:173], v[224:225], off offset:16
	global_load_dwordx4 v[174:177], v[224:225], off
	global_load_dwordx4 v[178:181], v[224:225], off offset:528
	global_load_dwordx4 v[182:185], v[224:225], off offset:512
	s_mov_b32 s98, 0x20000
	s_mov_b32 s99, 0
	v_lshl_add_u64 v[226:227], v[224:225], 0, s[98:99]
	global_load_dwordx4 v[186:189], v[226:227], off offset:16
	global_load_dwordx4 v[190:193], v[226:227], off
	s_mov_b32 s98, 0x20000
	s_mov_b32 s99, 0
	v_lshl_add_u64 v[226:227], v[224:225], 0, s[98:99]
	global_load_dwordx4 v[194:197], v[226:227], off offset:528
	global_load_dwordx4 v[198:201], v[226:227], off offset:512
	s_mov_b32 s98, 0x40000
	s_mov_b32 s99, 0
	v_lshl_add_u64 v[226:227], v[224:225], 0, s[98:99]
	global_load_dwordx4 v[202:205], v[226:227], off offset:16
	global_load_dwordx4 v[210:213], v[226:227], off
	s_mov_b32 s98, 0x40000
	s_mov_b32 s99, 0
	v_lshl_add_u64 v[226:227], v[224:225], 0, s[98:99]
	global_load_dwordx4 v[214:217], v[226:227], off offset:528
	global_load_dwordx4 v[218:221], v[226:227], off offset:512
	s_barrier
	ds_read_b32 v150, v156 offset:4096
	s_waitcnt vmcnt(10)
	s_nop 1
	v_mov_b32_e32 v158, v170
	v_mov_b32_e32 v159, v171
	v_mov_b32_e32 v160, v172
	v_mov_b32_e32 v161, v173
	v_mov_b32_e32 v162, v174
	v_mov_b32_e32 v163, v175
	v_mov_b32_e32 v164, v176
	v_mov_b32_e32 v165, v177
	s_mov_b32 s98, 0x60000
	s_mov_b32 s99, 0
	v_lshl_add_u64 v[226:227], v[224:225], 0, s[98:99]
	global_load_dwordx4 v[170:173], v[226:227], off offset:16
	global_load_dwordx4 v[174:177], v[226:227], off
	v_readlane_b32 s54, v254, 12
	v_readlane_b32 s55, v254, 13
	v_readlane_b32 s56, v254, 14
	s_waitcnt lgkmcnt(0)
	v_pk_mul_f32 v[140:141], v[140:141], v[150:151] op_sel_hi:[1,0]
	v_pk_mul_f32 v[142:143], v[142:143], v[150:151] op_sel_hi:[1,0]
	v_pk_mul_f32 v[136:137], v[136:137], v[150:151] op_sel_hi:[1,0]
	v_pk_mul_f32 v[138:139], v[138:139], v[150:151] op_sel_hi:[1,0]
	v_pk_mul_f32 v[132:133], v[132:133], v[150:151] op_sel_hi:[1,0]
	v_pk_mul_f32 v[128:129], v[128:129], v[150:151] op_sel_hi:[1,0]
	v_pk_mul_f32 v[130:131], v[130:131], v[150:151] op_sel_hi:[1,0]
	v_pk_mul_f32 v[134:135], v[134:135], v[150:151] op_sel_hi:[1,0]
	v_readlane_b32 s57, v254, 15
	v_readlane_b32 s58, v254, 16
	v_readlane_b32 s59, v254, 17
	v_readlane_b32 s60, v254, 18
	v_readlane_b32 s61, v254, 19
	v_readlane_b32 s62, v254, 20
	v_readlane_b32 s63, v254, 21
	v_readlane_b32 s64, v254, 22
	v_readlane_b32 s65, v254, 23
	v_readlane_b32 s66, v254, 24
	v_readlane_b32 s67, v254, 25
	v_pk_fma_f32 v[160:161], v[82:83], v[138:139], v[160:161]
	v_pk_fma_f32 v[140:141], v[84:85], v[140:141], v[162:163]
	v_pk_fma_f32 v[142:143], v[86:87], v[142:143], v[164:165]
	v_mul_f32_e32 v149, v141, v141
	v_fmac_f32_e32 v149, v140, v140
	v_fmac_f32_e32 v149, v142, v142
	v_pk_fma_f32 v[138:139], v[80:81], v[136:137], v[158:159]
	v_fmac_f32_e32 v149, v143, v143
	v_lshlrev_b64 v[158:159], 1, v[166:167]
	v_fmac_f32_e32 v149, v138, v138
	v_cvt_pk_bf16_f32 v136, v140, v141
	v_lshl_add_u64 v[140:141], s[68:69], 0, v[158:159]
	v_fmac_f32_e32 v149, v139, v139
	v_cvt_pk_bf16_f32 v137, v142, v143
	v_cvt_pk_bf16_f32 v138, v138, v139
	v_cvt_pk_bf16_f32 v139, v160, v161
	global_store_dwordx4 v[140:141], v[136:139], off
	s_waitcnt vmcnt(11)
	s_nop 1
	v_mov_b32_e32 v136, v178
	v_mov_b32_e32 v137, v179
	v_mov_b32_e32 v138, v180
	v_mov_b32_e32 v139, v181
	s_nop 0
	v_mov_b32_e32 v140, v182
	v_mov_b32_e32 v141, v183
	v_mov_b32_e32 v142, v184
	v_mov_b32_e32 v143, v185
	s_mov_b32 s98, 0x60000
	s_mov_b32 s99, 0
	v_lshl_add_u64 v[226:227], v[224:225], 0, s[98:99]
	global_load_dwordx4 v[178:181], v[226:227], off offset:528
	global_load_dwordx4 v[182:185], v[226:227], off offset:512
	v_fmac_f32_e32 v149, v160, v160
	v_fmac_f32_e32 v149, v161, v161
	v_or_b32_e32 v158, 0x100, v158
	v_pk_fma_f32 v[138:139], v[66:67], v[130:131], v[138:139]
	v_pk_fma_f32 v[132:133], v[68:69], v[132:133], v[140:141]
	v_pk_fma_f32 v[130:131], v[64:65], v[128:129], v[136:137]
	v_mul_f32_e32 v128, v133, v133
	v_pk_fma_f32 v[134:135], v[70:71], v[134:135], v[142:143]
	v_fmac_f32_e32 v128, v132, v132
	v_fmac_f32_e32 v128, v134, v134
	v_fmac_f32_e32 v128, v135, v135
	v_fmac_f32_e32 v128, v130, v130
	v_fmac_f32_e32 v128, v131, v131
	v_fmac_f32_e32 v128, v138, v138
	v_fmac_f32_e32 v128, v139, v139
	v_add_f32_e32 v136, v149, v128
	v_cvt_pk_bf16_f32 v128, v132, v133
	v_lshl_add_u64 v[132:133], s[68:69], 0, v[158:159]
	v_cvt_pk_bf16_f32 v129, v134, v135
	v_cvt_pk_bf16_f32 v130, v130, v131
	v_cvt_pk_bf16_f32 v131, v138, v139
	global_store_dwordx4 v[132:133], v[128:131], off
	ds_bpermute_b32 v128, v153, v136
	s_waitcnt lgkmcnt(0)
	v_add_f32_e32 v128, v136, v128
	ds_bpermute_b32 v129, v155, v128
	s_and_saveexec_b64 s[22:23], s[36:37]
	s_cbranch_execz .LBB0_686
	s_waitcnt lgkmcnt(0)
	v_add_f32_e32 v128, v128, v129
	ds_write_b32 v154, v128
; DI unsigned cvt_pk_bf16(float lo, float hi) { unsigned r; asm volatile("v_cvt_pk_bf16_f32 %0, %1, %2" : "=v"(r) : "v"(lo), "v"(hi)); return r; }
; DI float bf_lo(unsigned w) { return __uint_as_float(w << 16); }
; DI float bf_hi(unsigned w) { return __uint_as_float(w & 0xffff0000u); }
;   DI void fused(f32x4 (&acc)[2][2][4][2], const Unit& u, int wr, int wc, int, int, LAS unsigned char* lds, int tid_) const {
;     ...
; #pragma unroll
;     for (int ai = 0; ai < 2; ++ai) {
; #pragma unroll
;       for (int m = 0; m < 4; ++m) { const int rl = ai * HALF + m * 16 + rl0; const float r1 = rs[rl]; float ss = 0.f;
; #pragma unroll
;         for (int bj = 0; bj < 2; ++bj) { const size_t o = (size_t)(u.pm * BM + rl) * 2048 + col0 + bj * HALF;
;           f32x4 xa, xc;
;           if constexpr (XF32) { xa = *(const f32x4*)(xin32 + o); xc = *(const f32x4*)(xin32 + o + 4); }
;           else { const u32x4 w = xw[ai][m][bj]; xa = (f32x4){bf_lo(w.x), bf_hi(w.x), bf_lo(w.y), bf_hi(w.y)}; xc = (f32x4){bf_lo(w.z), bf_hi(w.z), bf_lo(w.w), bf_hi(w.w)}; }
;           const f32x4 t0 = xa + acc[ai][bj][m][0] * r1 * g0[bj], t1 = xc + acc[ai][bj][m][1] * r1 * g1[bj];
;           ss += t0[0] * t0[0] + t0[1] * t0[1] + t0[2] * t0[2] + t0[3] * t0[3] + t1[0] * t1[0] + t1[1] * t1[1] + t1[2] * t1[2] + t1[3] * t1[3];
;           if (xout32) { *(f32x4*)(xout32 + o) = t0; *(f32x4*)(xout32 + o + 4) = t1; }
;           else { u32x4 w; w.x = cvt_pk_bf16(t0[0], t0[1]); w.y = cvt_pk_bf16(t0[2], t0[3]); w.z = cvt_pk_bf16(t1[0], t1[1]); w.w = cvt_pk_bf16(t1[2], t1[3]); *(u32x4*)(xb + o) = w; } }
;         if (!xout32) { ss += __shfl_xor(ss, 16); ss += __shfl_xor(ss, 32); if (fq == 0) part[wc * 256 + rl] = ss; } }
.LBB0_686:
	s_or_b64 exec, exec, s[22:23]
	v_add3_u32 v130, s1, v157, 16
	v_ashrrev_i32_e32 v131, 31, v130
	v_lshlrev_b64 v[130:131], 11, v[130:131]
	v_readlane_b32 s52, v254, 10
	v_lshl_add_u64 v[138:139], v[130:131], 0, v[146:147]
	v_readlane_b32 s53, v254, 11
	ds_read_b32 v128, v156 offset:4160
	v_readlane_b32 s54, v254, 12
	v_lshl_add_u64 v[140:141], v[138:139], 2, s[52:53]
	s_waitcnt vmcnt(12)
	s_nop 1
	v_mov_b32_e32 v130, v186
	v_mov_b32_e32 v131, v187
	v_mov_b32_e32 v132, v188
	v_mov_b32_e32 v133, v189
	v_mov_b32_e32 v134, v190
	v_mov_b32_e32 v135, v191
	v_mov_b32_e32 v136, v192
	v_mov_b32_e32 v137, v193
	s_mov_b32 s98, 0x100000
	s_mov_b32 s99, 0
	v_lshl_add_u64 v[226:227], v[224:225], 0, s[98:99]
	global_load_dwordx4 v[186:189], v[226:227], off offset:16
	global_load_dwordx4 v[190:193], v[226:227], off
	v_readlane_b32 s55, v254, 13
	s_waitcnt lgkmcnt(0)
	v_pk_mul_f32 v[124:125], v[124:125], v[128:129] op_sel_hi:[1,0]
	v_pk_mul_f32 v[126:127], v[126:127], v[128:129] op_sel_hi:[1,0]
	v_pk_mul_f32 v[122:123], v[122:123], v[128:129] op_sel_hi:[1,0]
	v_pk_mul_f32 v[120:121], v[120:121], v[128:129] op_sel_hi:[1,0]
	v_readlane_b32 s56, v254, 14
	v_readlane_b32 s57, v254, 15
	v_readlane_b32 s58, v254, 16
	v_readlane_b32 s59, v254, 17
	v_readlane_b32 s60, v254, 18
	v_readlane_b32 s61, v254, 19
	v_readlane_b32 s62, v254, 20
	v_readlane_b32 s63, v254, 21
	v_readlane_b32 s64, v254, 22
	v_readlane_b32 s65, v254, 23
	v_readlane_b32 s66, v254, 24
	v_readlane_b32 s67, v254, 25
	v_pk_fma_f32 v[132:133], v[82:83], v[122:123], v[132:133]
	v_pk_fma_f32 v[124:125], v[84:85], v[124:125], v[134:135]
	v_pk_fma_f32 v[126:127], v[86:87], v[126:127], v[136:137]
	v_mul_f32_e32 v129, v125, v125
	v_fmac_f32_e32 v129, v124, v124
	v_fmac_f32_e32 v129, v126, v126
	v_pk_fma_f32 v[122:123], v[80:81], v[120:121], v[130:131]
	v_fmac_f32_e32 v129, v127, v127
	v_lshlrev_b64 v[130:131], 1, v[138:139]
	v_fmac_f32_e32 v129, v122, v122
	v_cvt_pk_bf16_f32 v120, v124, v125
	v_lshl_add_u64 v[124:125], s[68:69], 0, v[130:131]
	v_fmac_f32_e32 v129, v123, v123
	v_cvt_pk_bf16_f32 v121, v126, v127
	v_cvt_pk_bf16_f32 v122, v122, v123
	v_cvt_pk_bf16_f32 v123, v132, v133
	global_store_dwordx4 v[124:125], v[120:123], off
	s_waitcnt vmcnt(13)
	s_nop 1
	v_mov_b32_e32 v120, v194
	v_mov_b32_e32 v121, v195
	v_mov_b32_e32 v122, v196
	v_mov_b32_e32 v123, v197
	s_nop 0
	v_mov_b32_e32 v124, v198
	v_mov_b32_e32 v125, v199
	v_mov_b32_e32 v126, v200
	v_mov_b32_e32 v127, v201
	s_mov_b32 s98, 0x100000
	s_mov_b32 s99, 0
	v_lshl_add_u64 v[226:227], v[224:225], 0, s[98:99]
	global_load_dwordx4 v[194:197], v[226:227], off offset:528
	global_load_dwordx4 v[198:201], v[226:227], off offset:512
	v_fmac_f32_e32 v129, v132, v132
	v_fmac_f32_e32 v129, v133, v133
	v_pk_mul_f32 v[116:117], v[116:117], v[128:129] op_sel_hi:[1,0]
	v_pk_mul_f32 v[114:115], v[114:115], v[128:129] op_sel_hi:[1,0]
	v_pk_mul_f32 v[112:113], v[112:113], v[128:129] op_sel_hi:[1,0]
	v_pk_mul_f32 v[118:119], v[118:119], v[128:129] op_sel_hi:[1,0]
	v_or_b32_e32 v130, 0x100, v130
	v_pk_fma_f32 v[122:123], v[66:67], v[114:115], v[122:123]
	v_pk_fma_f32 v[116:117], v[68:69], v[116:117], v[124:125]
	v_pk_fma_f32 v[114:115], v[64:65], v[112:113], v[120:121]
	v_mul_f32_e32 v112, v117, v117
	v_pk_fma_f32 v[118:119], v[70:71], v[118:119], v[126:127]
	v_fmac_f32_e32 v112, v116, v116
	v_fmac_f32_e32 v112, v118, v118
	v_fmac_f32_e32 v112, v119, v119
	v_fmac_f32_e32 v112, v114, v114
	v_fmac_f32_e32 v112, v115, v115
	v_fmac_f32_e32 v112, v122, v122
	v_fmac_f32_e32 v112, v123, v123
	v_add_f32_e32 v120, v129, v112
	v_cvt_pk_bf16_f32 v112, v116, v117
	v_lshl_add_u64 v[116:117], s[68:69], 0, v[130:131]
	v_cvt_pk_bf16_f32 v113, v118, v119
	v_cvt_pk_bf16_f32 v114, v114, v115
	v_cvt_pk_bf16_f32 v115, v122, v123
	global_store_dwordx4 v[116:117], v[112:115], off
	ds_bpermute_b32 v112, v153, v120
	s_waitcnt lgkmcnt(0)
	v_add_f32_e32 v112, v120, v112
	ds_bpermute_b32 v113, v155, v112
	s_and_saveexec_b64 s[22:23], s[36:37]
	s_cbranch_execz .LBB0_688
	s_waitcnt lgkmcnt(0)
	v_add_f32_e32 v112, v112, v113
	ds_write_b32 v154, v112 offset:64
.LBB0_688:
	s_or_b64 exec, exec, s[22:23]
	v_add3_u32 v114, s1, v157, 32
	v_ashrrev_i32_e32 v115, 31, v114
	v_lshlrev_b64 v[114:115], 11, v[114:115]
	v_readlane_b32 s52, v254, 10
	v_lshl_add_u64 v[122:123], v[114:115], 0, v[146:147]
	v_readlane_b32 s53, v254, 11
	ds_read_b32 v112, v156 offset:4224
	v_readlane_b32 s54, v254, 12
	v_lshl_add_u64 v[124:125], v[122:123], 2, s[52:53]
	s_waitcnt vmcnt(14)
	s_nop 1
	v_mov_b32_e32 v114, v202
	v_mov_b32_e32 v115, v203
	v_mov_b32_e32 v116, v204
	v_mov_b32_e32 v117, v205
	v_mov_b32_e32 v118, v210
	v_mov_b32_e32 v119, v211
	v_mov_b32_e32 v120, v212
	v_mov_b32_e32 v121, v213
	s_mov_b32 s98, 0x120000
	s_mov_b32 s99, 0
	v_lshl_add_u64 v[226:227], v[224:225], 0, s[98:99]
	global_load_dwordx4 v[202:205], v[226:227], off offset:16
	global_load_dwordx4 v[210:213], v[226:227], off
	v_readlane_b32 s55, v254, 13
	s_waitcnt lgkmcnt(0)
; DI unsigned cvt_pk_bf16(float lo, float hi) { unsigned r; asm volatile("v_cvt_pk_bf16_f32 %0, %1, %2" : "=v"(r) : "v"(lo), "v"(hi)); return r; }
; DI float bf_lo(unsigned w) { return __uint_as_float(w << 16); }
; DI float bf_hi(unsigned w) { return __uint_as_float(w & 0xffff0000u); }
;   DI void fused(f32x4 (&acc)[2][2][4][2], const Unit& u, int wr, int wc, int, int, LAS unsigned char* lds, int tid_) const {
;     ...
; #pragma unroll
;     for (int ai = 0; ai < 2; ++ai) {
; #pragma unroll
;       for (int m = 0; m < 4; ++m) { const int rl = ai * HALF + m * 16 + rl0; const float r1 = rs[rl]; float ss = 0.f;
; #pragma unroll
;         for (int bj = 0; bj < 2; ++bj) { const size_t o = (size_t)(u.pm * BM + rl) * 2048 + col0 + bj * HALF;
;           f32x4 xa, xc;
;           if constexpr (XF32) { xa = *(const f32x4*)(xin32 + o); xc = *(const f32x4*)(xin32 + o + 4); }
;           else { const u32x4 w = xw[ai][m][bj]; xa = (f32x4){bf_lo(w.x), bf_hi(w.x), bf_lo(w.y), bf_hi(w.y)}; xc = (f32x4){bf_lo(w.z), bf_hi(w.z), bf_lo(w.w), bf_hi(w.w)}; }
;           const f32x4 t0 = xa + acc[ai][bj][m][0] * r1 * g0[bj], t1 = xc + acc[ai][bj][m][1] * r1 * g1[bj];
;           ss += t0[0] * t0[0] + t0[1] * t0[1] + t0[2] * t0[2] + t0[3] * t0[3] + t1[0] * t1[0] + t1[1] * t1[1] + t1[2] * t1[2] + t1[3] * t1[3];
;           if (xout32) { *(f32x4*)(xout32 + o) = t0; *(f32x4*)(xout32 + o + 4) = t1; }
;           else { u32x4 w; w.x = cvt_pk_bf16(t0[0], t0[1]); w.y = cvt_pk_bf16(t0[2], t0[3]); w.z = cvt_pk_bf16(t1[0], t1[1]); w.w = cvt_pk_bf16(t1[2], t1[3]); *(u32x4*)(xb + o) = w; } }
;         if (!xout32) { ss += __shfl_xor(ss, 16); ss += __shfl_xor(ss, 32); if (fq == 0) part[wc * 256 + rl] = ss; } }
	v_pk_mul_f32 v[108:109], v[108:109], v[112:113] op_sel_hi:[1,0]
	v_pk_mul_f32 v[110:111], v[110:111], v[112:113] op_sel_hi:[1,0]
	v_pk_mul_f32 v[106:107], v[106:107], v[112:113] op_sel_hi:[1,0]
	v_pk_mul_f32 v[104:105], v[104:105], v[112:113] op_sel_hi:[1,0]
	v_readlane_b32 s56, v254, 14
	v_readlane_b32 s57, v254, 15
	v_readlane_b32 s58, v254, 16
	v_readlane_b32 s59, v254, 17
	v_readlane_b32 s60, v254, 18
	v_readlane_b32 s61, v254, 19
	v_readlane_b32 s62, v254, 20
	v_readlane_b32 s63, v254, 21
	v_readlane_b32 s64, v254, 22
	v_readlane_b32 s65, v254, 23
	v_readlane_b32 s66, v254, 24
	v_readlane_b32 s67, v254, 25
	v_pk_fma_f32 v[116:117], v[82:83], v[106:107], v[116:117]
	v_pk_fma_f32 v[108:109], v[84:85], v[108:109], v[118:119]
	v_pk_fma_f32 v[110:111], v[86:87], v[110:111], v[120:121]
	v_mul_f32_e32 v113, v109, v109
	v_fmac_f32_e32 v113, v108, v108
	v_fmac_f32_e32 v113, v110, v110
	v_pk_fma_f32 v[106:107], v[80:81], v[104:105], v[114:115]
	v_fmac_f32_e32 v113, v111, v111
	v_lshlrev_b64 v[114:115], 1, v[122:123]
	v_fmac_f32_e32 v113, v106, v106
	v_cvt_pk_bf16_f32 v104, v108, v109
	v_lshl_add_u64 v[108:109], s[68:69], 0, v[114:115]
	v_fmac_f32_e32 v113, v107, v107
	v_cvt_pk_bf16_f32 v105, v110, v111
	v_cvt_pk_bf16_f32 v106, v106, v107
	v_cvt_pk_bf16_f32 v107, v116, v117
	global_store_dwordx4 v[108:109], v[104:107], off
	s_waitcnt vmcnt(15)
	s_nop 1
	v_mov_b32_e32 v104, v214
	v_mov_b32_e32 v105, v215
	v_mov_b32_e32 v106, v216
	v_mov_b32_e32 v107, v217
	s_nop 0
	v_mov_b32_e32 v108, v218
	v_mov_b32_e32 v109, v219
	v_mov_b32_e32 v110, v220
	v_mov_b32_e32 v111, v221
	s_mov_b32 s98, 0x120000
	s_mov_b32 s99, 0
	v_lshl_add_u64 v[226:227], v[224:225], 0, s[98:99]
	global_load_dwordx4 v[214:217], v[226:227], off offset:528
	global_load_dwordx4 v[218:221], v[226:227], off offset:512
	v_fmac_f32_e32 v113, v116, v116
	v_fmac_f32_e32 v113, v117, v117
	v_pk_mul_f32 v[100:101], v[100:101], v[112:113] op_sel_hi:[1,0]
	v_pk_mul_f32 v[98:99], v[98:99], v[112:113] op_sel_hi:[1,0]
	v_pk_mul_f32 v[96:97], v[96:97], v[112:113] op_sel_hi:[1,0]
	v_pk_mul_f32 v[102:103], v[102:103], v[112:113] op_sel_hi:[1,0]
	v_or_b32_e32 v114, 0x100, v114
	v_pk_fma_f32 v[106:107], v[66:67], v[98:99], v[106:107]
	v_pk_fma_f32 v[100:101], v[68:69], v[100:101], v[108:109]
	v_pk_fma_f32 v[98:99], v[64:65], v[96:97], v[104:105]
	v_mul_f32_e32 v96, v101, v101
	v_pk_fma_f32 v[102:103], v[70:71], v[102:103], v[110:111]
	v_fmac_f32_e32 v96, v100, v100
	v_fmac_f32_e32 v96, v102, v102
	v_fmac_f32_e32 v96, v103, v103
	v_fmac_f32_e32 v96, v98, v98
	v_fmac_f32_e32 v96, v99, v99
	v_fmac_f32_e32 v96, v106, v106
	v_fmac_f32_e32 v96, v107, v107
	v_add_f32_e32 v104, v113, v96
	v_cvt_pk_bf16_f32 v96, v100, v101
	v_lshl_add_u64 v[100:101], s[68:69], 0, v[114:115]
	v_cvt_pk_bf16_f32 v97, v102, v103
	v_cvt_pk_bf16_f32 v98, v98, v99
	v_cvt_pk_bf16_f32 v99, v106, v107
	global_store_dwordx4 v[100:101], v[96:99], off
	ds_bpermute_b32 v96, v153, v104
	s_waitcnt lgkmcnt(0)
	v_add_f32_e32 v96, v104, v96
	ds_bpermute_b32 v97, v155, v96
	s_and_saveexec_b64 s[22:23], s[36:37]
	s_cbranch_execz .LBB0_690
	s_waitcnt lgkmcnt(0)
	v_add_f32_e32 v96, v96, v97
	ds_write_b32 v154, v96 offset:128
.LBB0_690:
	s_or_b64 exec, exec, s[22:23]
	v_add3_u32 v96, s1, v157, 48
	s_waitcnt lgkmcnt(0)
	v_ashrrev_i32_e32 v97, 31, v96
	v_lshlrev_b64 v[96:97], 11, v[96:97]
	v_readlane_b32 s52, v254, 10
	v_lshl_add_u64 v[106:107], v[96:97], 0, v[146:147]
	v_readlane_b32 s53, v254, 11
	ds_read_b32 v104, v156 offset:4288
	v_readlane_b32 s54, v254, 12
	v_lshl_add_u64 v[108:109], v[106:107], 2, s[52:53]
	s_waitcnt vmcnt(16)
	s_nop 1
	v_mov_b32_e32 v96, v170
	v_mov_b32_e32 v97, v171
	v_mov_b32_e32 v98, v172
	v_mov_b32_e32 v99, v173
	v_mov_b32_e32 v100, v174
	v_mov_b32_e32 v101, v175
	v_mov_b32_e32 v102, v176
	v_mov_b32_e32 v103, v177
	s_mov_b32 s98, 0x140000
	s_mov_b32 s99, 0
	v_lshl_add_u64 v[226:227], v[224:225], 0, s[98:99]
	global_load_dwordx4 v[170:173], v[226:227], off offset:16
	global_load_dwordx4 v[174:177], v[226:227], off
	v_readlane_b32 s55, v254, 13
	s_waitcnt lgkmcnt(0)
	v_pk_mul_f32 v[92:93], v[92:93], v[104:105] op_sel_hi:[1,0]
	v_pk_mul_f32 v[94:95], v[94:95], v[104:105] op_sel_hi:[1,0]
	v_pk_mul_f32 v[90:91], v[90:91], v[104:105] op_sel_hi:[1,0]
	v_pk_mul_f32 v[88:89], v[88:89], v[104:105] op_sel_hi:[1,0]
	v_pk_mul_f32 v[76:77], v[76:77], v[104:105] op_sel_hi:[1,0]
	v_pk_mul_f32 v[74:75], v[74:75], v[104:105] op_sel_hi:[1,0]
	v_pk_mul_f32 v[72:73], v[72:73], v[104:105] op_sel_hi:[1,0]
	v_pk_mul_f32 v[78:79], v[78:79], v[104:105] op_sel_hi:[1,0]
	v_readlane_b32 s56, v254, 14
	v_readlane_b32 s57, v254, 15
	v_readlane_b32 s58, v254, 16
	v_readlane_b32 s59, v254, 17
	v_readlane_b32 s60, v254, 18
	v_readlane_b32 s61, v254, 19
	v_readlane_b32 s62, v254, 20
	v_readlane_b32 s63, v254, 21
	v_readlane_b32 s64, v254, 22
	v_readlane_b32 s65, v254, 23
	v_readlane_b32 s66, v254, 24
	v_readlane_b32 s67, v254, 25
	v_pk_fma_f32 v[98:99], v[82:83], v[90:91], v[98:99]
	v_pk_fma_f32 v[92:93], v[84:85], v[92:93], v[100:101]
	v_pk_fma_f32 v[94:95], v[86:87], v[94:95], v[102:103]
	v_mul_f32_e32 v100, v93, v93
	v_fmac_f32_e32 v100, v92, v92
	v_fmac_f32_e32 v100, v94, v94
	v_pk_fma_f32 v[90:91], v[80:81], v[88:89], v[96:97]
	v_fmac_f32_e32 v100, v95, v95
	v_lshlrev_b64 v[96:97], 1, v[106:107]
	v_fmac_f32_e32 v100, v90, v90
	v_cvt_pk_bf16_f32 v88, v92, v93
	v_lshl_add_u64 v[92:93], s[68:69], 0, v[96:97]
	v_fmac_f32_e32 v100, v91, v91
	v_cvt_pk_bf16_f32 v89, v94, v95
	v_cvt_pk_bf16_f32 v90, v90, v91
	v_cvt_pk_bf16_f32 v91, v98, v99
	global_store_dwordx4 v[92:93], v[88:91], off
	s_waitcnt vmcnt(16)
	s_nop 1
	v_mov_b32_e32 v88, v178
	v_mov_b32_e32 v89, v179
	v_mov_b32_e32 v90, v180
	v_mov_b32_e32 v91, v181
	s_nop 0
	v_mov_b32_e32 v92, v182
	v_mov_b32_e32 v93, v183
	v_mov_b32_e32 v94, v184
	v_mov_b32_e32 v95, v185
	s_mov_b32 s98, 0x140000
	s_mov_b32 s99, 0
	v_lshl_add_u64 v[226:227], v[224:225], 0, s[98:99]
	global_load_dwordx4 v[178:181], v[226:227], off offset:528
	global_load_dwordx4 v[182:185], v[226:227], off offset:512
	v_fmac_f32_e32 v100, v98, v98
	v_fmac_f32_e32 v100, v99, v99
	v_or_b32_e32 v96, 0x100, v96
	v_pk_fma_f32 v[90:91], v[66:67], v[74:75], v[90:91]
	v_pk_fma_f32 v[76:77], v[68:69], v[76:77], v[92:93]
	v_pk_fma_f32 v[74:75], v[64:65], v[72:73], v[88:89]
	v_mul_f32_e32 v72, v77, v77
	v_pk_fma_f32 v[78:79], v[70:71], v[78:79], v[94:95]
	v_fmac_f32_e32 v72, v76, v76
	v_fmac_f32_e32 v72, v78, v78
	v_fmac_f32_e32 v72, v79, v79
	v_fmac_f32_e32 v72, v74, v74
	v_fmac_f32_e32 v72, v75, v75
	v_fmac_f32_e32 v72, v90, v90
	v_fmac_f32_e32 v72, v91, v91
	v_add_f32_e32 v88, v100, v72
	v_cvt_pk_bf16_f32 v72, v76, v77
	v_lshl_add_u64 v[76:77], s[68:69], 0, v[96:97]
	v_cvt_pk_bf16_f32 v73, v78, v79
	v_cvt_pk_bf16_f32 v74, v74, v75
	v_cvt_pk_bf16_f32 v75, v90, v91
	global_store_dwordx4 v[76:77], v[72:75], off
	ds_bpermute_b32 v72, v153, v88
	s_waitcnt lgkmcnt(0)
	v_add_f32_e32 v72, v88, v72
	ds_bpermute_b32 v73, v155, v72
	s_and_saveexec_b64 s[22:23], s[36:37]
	s_cbranch_execz .LBB0_692
; DI unsigned cvt_pk_bf16(float lo, float hi) { unsigned r; asm volatile("v_cvt_pk_bf16_f32 %0, %1, %2" : "=v"(r) : "v"(lo), "v"(hi)); return r; }
; DI float bf_lo(unsigned w) { return __uint_as_float(w << 16); }
; DI float bf_hi(unsigned w) { return __uint_as_float(w & 0xffff0000u); }
;   DI void fused(f32x4 (&acc)[2][2][4][2], const Unit& u, int wr, int wc, int, int, LAS unsigned char* lds, int tid_) const {
;     ...
; #pragma unroll
;     for (int ai = 0; ai < 2; ++ai) {
; #pragma unroll
;       for (int m = 0; m < 4; ++m) { const int rl = ai * HALF + m * 16 + rl0; const float r1 = rs[rl]; float ss = 0.f;
; #pragma unroll
;         for (int bj = 0; bj < 2; ++bj) { const size_t o = (size_t)(u.pm * BM + rl) * 2048 + col0 + bj * HALF;
;           f32x4 xa, xc;
;           if constexpr (XF32) { xa = *(const f32x4*)(xin32 + o); xc = *(const f32x4*)(xin32 + o + 4); }
;           else { const u32x4 w = xw[ai][m][bj]; xa = (f32x4){bf_lo(w.x), bf_hi(w.x), bf_lo(w.y), bf_hi(w.y)}; xc = (f32x4){bf_lo(w.z), bf_hi(w.z), bf_lo(w.w), bf_hi(w.w)}; }
;           const f32x4 t0 = xa + acc[ai][bj][m][0] * r1 * g0[bj], t1 = xc + acc[ai][bj][m][1] * r1 * g1[bj];
;           ss += t0[0] * t0[0] + t0[1] * t0[1] + t0[2] * t0[2] + t0[3] * t0[3] + t1[0] * t1[0] + t1[1] * t1[1] + t1[2] * t1[2] + t1[3] * t1[3];
;           if (xout32) { *(f32x4*)(xout32 + o) = t0; *(f32x4*)(xout32 + o + 4) = t1; }
;           else { u32x4 w; w.x = cvt_pk_bf16(t0[0], t0[1]); w.y = cvt_pk_bf16(t0[2], t0[3]); w.z = cvt_pk_bf16(t1[0], t1[1]); w.w = cvt_pk_bf16(t1[2], t1[3]); *(u32x4*)(xb + o) = w; } }
;         if (!xout32) { ss += __shfl_xor(ss, 16); ss += __shfl_xor(ss, 32); if (fq == 0) part[wc * 256 + rl] = ss; } }
	s_waitcnt lgkmcnt(0)
	v_add_f32_e32 v72, v72, v73
	ds_write_b32 v154, v72 offset:192
.LBB0_692:
	s_or_b64 exec, exec, s[22:23]
	v_add_u32_e32 v74, 0x80, v148
	v_ashrrev_i32_e32 v75, 31, v74
	v_lshlrev_b64 v[74:75], 11, v[74:75]
	v_readlane_b32 s52, v254, 10
	v_lshl_add_u64 v[78:79], v[74:75], 0, v[146:147]
	v_readlane_b32 s53, v254, 11
	ds_read_b32 v72, v156 offset:4608
	v_readlane_b32 s54, v254, 12
	v_lshl_add_u64 v[92:93], v[78:79], 2, s[52:53]
	s_waitcnt vmcnt(16)
	s_nop 1
	v_mov_b32_e32 v74, v186
	v_mov_b32_e32 v75, v187
	v_mov_b32_e32 v76, v188
	v_mov_b32_e32 v77, v189
	v_mov_b32_e32 v88, v190
	v_mov_b32_e32 v89, v191
	v_mov_b32_e32 v90, v192
	v_mov_b32_e32 v91, v193
	s_mov_b32 s98, 0x160000
	s_mov_b32 s99, 0
	v_lshl_add_u64 v[226:227], v[224:225], 0, s[98:99]
	global_load_dwordx4 v[186:189], v[226:227], off offset:16
	global_load_dwordx4 v[190:193], v[226:227], off
	v_readlane_b32 s55, v254, 13
	s_waitcnt lgkmcnt(0)
	v_pk_mul_f32 v[60:61], v[60:61], v[72:73] op_sel_hi:[1,0]
	v_pk_mul_f32 v[62:63], v[62:63], v[72:73] op_sel_hi:[1,0]
	v_pk_mul_f32 v[58:59], v[58:59], v[72:73] op_sel_hi:[1,0]
	v_pk_mul_f32 v[56:57], v[56:57], v[72:73] op_sel_hi:[1,0]
	v_readlane_b32 s56, v254, 14
	v_readlane_b32 s57, v254, 15
	v_readlane_b32 s58, v254, 16
	v_readlane_b32 s59, v254, 17
	v_readlane_b32 s60, v254, 18
	v_readlane_b32 s61, v254, 19
	v_readlane_b32 s62, v254, 20
	v_readlane_b32 s63, v254, 21
	v_readlane_b32 s64, v254, 22
	v_readlane_b32 s65, v254, 23
	v_readlane_b32 s66, v254, 24
	v_readlane_b32 s67, v254, 25
	v_pk_fma_f32 v[76:77], v[82:83], v[58:59], v[76:77]
	v_pk_fma_f32 v[60:61], v[84:85], v[60:61], v[88:89]
	v_pk_fma_f32 v[62:63], v[86:87], v[62:63], v[90:91]
	v_mul_f32_e32 v73, v61, v61
	v_fmac_f32_e32 v73, v60, v60
	v_fmac_f32_e32 v73, v62, v62
	v_pk_fma_f32 v[58:59], v[80:81], v[56:57], v[74:75]
	v_fmac_f32_e32 v73, v63, v63
	v_lshlrev_b64 v[74:75], 1, v[78:79]
	v_fmac_f32_e32 v73, v58, v58
	v_cvt_pk_bf16_f32 v56, v60, v61
	v_lshl_add_u64 v[60:61], s[68:69], 0, v[74:75]
	v_fmac_f32_e32 v73, v59, v59
	v_cvt_pk_bf16_f32 v57, v62, v63
	v_cvt_pk_bf16_f32 v58, v58, v59
	v_cvt_pk_bf16_f32 v59, v76, v77
	global_store_dwordx4 v[60:61], v[56:59], off
	s_waitcnt vmcnt(16)
	s_nop 1
	v_mov_b32_e32 v56, v194
	v_mov_b32_e32 v57, v195
	v_mov_b32_e32 v58, v196
	v_mov_b32_e32 v59, v197
	s_nop 0
	v_mov_b32_e32 v60, v198
	v_mov_b32_e32 v61, v199
	v_mov_b32_e32 v62, v200
	v_mov_b32_e32 v63, v201
	s_mov_b32 s98, 0x160000
	s_mov_b32 s99, 0
	v_lshl_add_u64 v[226:227], v[224:225], 0, s[98:99]
	global_load_dwordx4 v[194:197], v[226:227], off offset:528
	global_load_dwordx4 v[198:201], v[226:227], off offset:512
	v_fmac_f32_e32 v73, v76, v76
	v_fmac_f32_e32 v73, v77, v77
	v_pk_mul_f32 v[52:53], v[52:53], v[72:73] op_sel_hi:[1,0]
	v_pk_mul_f32 v[50:51], v[50:51], v[72:73] op_sel_hi:[1,0]
	v_pk_mul_f32 v[48:49], v[48:49], v[72:73] op_sel_hi:[1,0]
	v_pk_mul_f32 v[54:55], v[54:55], v[72:73] op_sel_hi:[1,0]
	v_or_b32_e32 v74, 0x100, v74
	v_pk_fma_f32 v[58:59], v[66:67], v[50:51], v[58:59]
	v_pk_fma_f32 v[52:53], v[68:69], v[52:53], v[60:61]
	v_pk_fma_f32 v[50:51], v[64:65], v[48:49], v[56:57]
	v_mul_f32_e32 v48, v53, v53
	v_pk_fma_f32 v[54:55], v[70:71], v[54:55], v[62:63]
	v_fmac_f32_e32 v48, v52, v52
	v_fmac_f32_e32 v48, v54, v54
	v_fmac_f32_e32 v48, v55, v55
	v_fmac_f32_e32 v48, v50, v50
	v_fmac_f32_e32 v48, v51, v51
	v_fmac_f32_e32 v48, v58, v58
	v_fmac_f32_e32 v48, v59, v59
	v_add_f32_e32 v56, v73, v48
	v_cvt_pk_bf16_f32 v48, v52, v53
	v_lshl_add_u64 v[52:53], s[68:69], 0, v[74:75]
	v_cvt_pk_bf16_f32 v49, v54, v55
	v_cvt_pk_bf16_f32 v50, v50, v51
	v_cvt_pk_bf16_f32 v51, v58, v59
	global_store_dwordx4 v[52:53], v[48:51], off
	ds_bpermute_b32 v48, v153, v56
	s_waitcnt lgkmcnt(0)
	v_add_f32_e32 v48, v56, v48
	ds_bpermute_b32 v49, v155, v48
	s_and_saveexec_b64 s[22:23], s[36:37]
	s_cbranch_execz .LBB0_694
	s_waitcnt lgkmcnt(0)
	v_add_f32_e32 v48, v48, v49
	ds_write_b32 v154, v48 offset:512
.LBB0_694:
	s_or_b64 exec, exec, s[22:23]
	v_add_u32_e32 v48, 0x90, v148
	s_waitcnt lgkmcnt(0)
	v_ashrrev_i32_e32 v49, 31, v48
	v_lshlrev_b64 v[48:49], 11, v[48:49]
	v_readlane_b32 s52, v254, 10
	v_lshl_add_u64 v[58:59], v[48:49], 0, v[146:147]
	v_readlane_b32 s53, v254, 11
	ds_read_b32 v56, v156 offset:4672
	v_readlane_b32 s54, v254, 12
	v_lshl_add_u64 v[60:61], v[58:59], 2, s[52:53]
	s_waitcnt vmcnt(16)
	s_nop 1
	v_mov_b32_e32 v48, v202
	v_mov_b32_e32 v49, v203
	v_mov_b32_e32 v50, v204
	v_mov_b32_e32 v51, v205
	v_mov_b32_e32 v52, v210
	v_mov_b32_e32 v53, v211
	v_mov_b32_e32 v54, v212
	v_mov_b32_e32 v55, v213
	v_readlane_b32 s55, v254, 13
	s_waitcnt lgkmcnt(0)
	v_pk_mul_f32 v[44:45], v[44:45], v[56:57] op_sel_hi:[1,0]
	v_pk_mul_f32 v[46:47], v[46:47], v[56:57] op_sel_hi:[1,0]
	v_pk_mul_f32 v[42:43], v[42:43], v[56:57] op_sel_hi:[1,0]
	v_pk_mul_f32 v[40:41], v[40:41], v[56:57] op_sel_hi:[1,0]
	v_pk_mul_f32 v[36:37], v[36:37], v[56:57] op_sel_hi:[1,0]
	v_pk_mul_f32 v[34:35], v[34:35], v[56:57] op_sel_hi:[1,0]
	v_pk_mul_f32 v[32:33], v[32:33], v[56:57] op_sel_hi:[1,0]
	v_pk_mul_f32 v[38:39], v[38:39], v[56:57] op_sel_hi:[1,0]
	v_readlane_b32 s56, v254, 14
	v_readlane_b32 s57, v254, 15
	v_readlane_b32 s58, v254, 16
	v_readlane_b32 s59, v254, 17
	v_readlane_b32 s60, v254, 18
	v_readlane_b32 s61, v254, 19
	v_readlane_b32 s62, v254, 20
	v_readlane_b32 s63, v254, 21
	v_readlane_b32 s64, v254, 22
	v_readlane_b32 s65, v254, 23
	v_readlane_b32 s66, v254, 24
	v_readlane_b32 s67, v254, 25
	v_pk_fma_f32 v[50:51], v[82:83], v[42:43], v[50:51]
	v_pk_fma_f32 v[44:45], v[84:85], v[44:45], v[52:53]
	v_pk_fma_f32 v[46:47], v[86:87], v[46:47], v[54:55]
	v_mul_f32_e32 v52, v45, v45
	v_fmac_f32_e32 v52, v44, v44
	v_fmac_f32_e32 v52, v46, v46
	v_pk_fma_f32 v[42:43], v[80:81], v[40:41], v[48:49]
	v_fmac_f32_e32 v52, v47, v47
	v_lshlrev_b64 v[48:49], 1, v[58:59]
	v_fmac_f32_e32 v52, v42, v42
	v_cvt_pk_bf16_f32 v40, v44, v45
	v_lshl_add_u64 v[44:45], s[68:69], 0, v[48:49]
	v_fmac_f32_e32 v52, v43, v43
	v_cvt_pk_bf16_f32 v41, v46, v47
	v_cvt_pk_bf16_f32 v42, v42, v43
	v_cvt_pk_bf16_f32 v43, v50, v51
	global_store_dwordx4 v[44:45], v[40:43], off
	s_waitcnt vmcnt(14)
; DI unsigned cvt_pk_bf16(float lo, float hi) { unsigned r; asm volatile("v_cvt_pk_bf16_f32 %0, %1, %2" : "=v"(r) : "v"(lo), "v"(hi)); return r; }
; DI float bf_lo(unsigned w) { return __uint_as_float(w << 16); }
; DI float bf_hi(unsigned w) { return __uint_as_float(w & 0xffff0000u); }
;   DI void fused(f32x4 (&acc)[2][2][4][2], const Unit& u, int wr, int wc, int, int, LAS unsigned char* lds, int tid_) const {
;     ...
; #pragma unroll
;     for (int ai = 0; ai < 2; ++ai) {
; #pragma unroll
;       for (int m = 0; m < 4; ++m) { const int rl = ai * HALF + m * 16 + rl0; const float r1 = rs[rl]; float ss = 0.f;
; #pragma unroll
;         for (int bj = 0; bj < 2; ++bj) { const size_t o = (size_t)(u.pm * BM + rl) * 2048 + col0 + bj * HALF;
;           f32x4 xa, xc;
;           if constexpr (XF32) { xa = *(const f32x4*)(xin32 + o); xc = *(const f32x4*)(xin32 + o + 4); }
;           else { const u32x4 w = xw[ai][m][bj]; xa = (f32x4){bf_lo(w.x), bf_hi(w.x), bf_lo(w.y), bf_hi(w.y)}; xc = (f32x4){bf_lo(w.z), bf_hi(w.z), bf_lo(w.w), bf_hi(w.w)}; }
;           const f32x4 t0 = xa + acc[ai][bj][m][0] * r1 * g0[bj], t1 = xc + acc[ai][bj][m][1] * r1 * g1[bj];
;           ss += t0[0] * t0[0] + t0[1] * t0[1] + t0[2] * t0[2] + t0[3] * t0[3] + t1[0] * t1[0] + t1[1] * t1[1] + t1[2] * t1[2] + t1[3] * t1[3];
;           if (xout32) { *(f32x4*)(xout32 + o) = t0; *(f32x4*)(xout32 + o + 4) = t1; }
;           else { u32x4 w; w.x = cvt_pk_bf16(t0[0], t0[1]); w.y = cvt_pk_bf16(t0[2], t0[3]); w.z = cvt_pk_bf16(t1[0], t1[1]); w.w = cvt_pk_bf16(t1[2], t1[3]); *(u32x4*)(xb + o) = w; } }
;         if (!xout32) { ss += __shfl_xor(ss, 16); ss += __shfl_xor(ss, 32); if (fq == 0) part[wc * 256 + rl] = ss; } }
	s_nop 1
	v_mov_b32_e32 v40, v214
	v_mov_b32_e32 v41, v215
	v_mov_b32_e32 v42, v216
	v_mov_b32_e32 v43, v217
	s_nop 0
	v_mov_b32_e32 v44, v218
	v_mov_b32_e32 v45, v219
	v_mov_b32_e32 v46, v220
	v_mov_b32_e32 v47, v221
	v_fmac_f32_e32 v52, v50, v50
	v_fmac_f32_e32 v52, v51, v51
	v_or_b32_e32 v48, 0x100, v48
	v_pk_fma_f32 v[42:43], v[66:67], v[34:35], v[42:43]
	v_pk_fma_f32 v[36:37], v[68:69], v[36:37], v[44:45]
	v_pk_fma_f32 v[34:35], v[64:65], v[32:33], v[40:41]
	v_mul_f32_e32 v32, v37, v37
	v_pk_fma_f32 v[38:39], v[70:71], v[38:39], v[46:47]
	v_fmac_f32_e32 v32, v36, v36
	v_fmac_f32_e32 v32, v38, v38
	v_fmac_f32_e32 v32, v39, v39
	v_fmac_f32_e32 v32, v34, v34
	v_fmac_f32_e32 v32, v35, v35
	v_fmac_f32_e32 v32, v42, v42
	v_fmac_f32_e32 v32, v43, v43
	v_add_f32_e32 v40, v52, v32
	v_cvt_pk_bf16_f32 v32, v36, v37
	v_lshl_add_u64 v[36:37], s[68:69], 0, v[48:49]
	v_cvt_pk_bf16_f32 v33, v38, v39
	v_cvt_pk_bf16_f32 v34, v34, v35
	v_cvt_pk_bf16_f32 v35, v42, v43
	global_store_dwordx4 v[36:37], v[32:35], off
	ds_bpermute_b32 v32, v153, v40
	s_waitcnt lgkmcnt(0)
	v_add_f32_e32 v32, v40, v32
	ds_bpermute_b32 v33, v155, v32
	s_and_saveexec_b64 s[22:23], s[36:37]
	s_cbranch_execz .LBB0_696
	s_waitcnt lgkmcnt(0)
	v_add_f32_e32 v32, v32, v33
	ds_write_b32 v154, v32 offset:576
.LBB0_696:
	s_or_b64 exec, exec, s[22:23]
	v_add_u32_e32 v34, 0xa0, v148
	v_ashrrev_i32_e32 v35, 31, v34
	v_lshlrev_b64 v[34:35], 11, v[34:35]
	v_readlane_b32 s52, v254, 10
	v_lshl_add_u64 v[42:43], v[34:35], 0, v[146:147]
	v_readlane_b32 s53, v254, 11
	ds_read_b32 v32, v156 offset:4736
	v_readlane_b32 s54, v254, 12
	v_lshl_add_u64 v[44:45], v[42:43], 2, s[52:53]
	s_waitcnt vmcnt(12)
	s_nop 1
	v_mov_b32_e32 v34, v170
	v_mov_b32_e32 v35, v171
	v_mov_b32_e32 v36, v172
	v_mov_b32_e32 v37, v173
	v_mov_b32_e32 v38, v174
	v_mov_b32_e32 v39, v175
	v_mov_b32_e32 v40, v176
	v_mov_b32_e32 v41, v177
	v_readlane_b32 s55, v254, 13
	s_waitcnt lgkmcnt(0)
	v_pk_mul_f32 v[28:29], v[28:29], v[32:33] op_sel_hi:[1,0]
	v_pk_mul_f32 v[30:31], v[30:31], v[32:33] op_sel_hi:[1,0]
	v_pk_mul_f32 v[26:27], v[26:27], v[32:33] op_sel_hi:[1,0]
	v_pk_mul_f32 v[24:25], v[24:25], v[32:33] op_sel_hi:[1,0]
	v_readlane_b32 s56, v254, 14
	v_readlane_b32 s57, v254, 15
	v_readlane_b32 s58, v254, 16
	v_readlane_b32 s59, v254, 17
	v_readlane_b32 s60, v254, 18
	v_readlane_b32 s61, v254, 19
	v_readlane_b32 s62, v254, 20
	v_readlane_b32 s63, v254, 21
	v_readlane_b32 s64, v254, 22
	v_readlane_b32 s65, v254, 23
	v_readlane_b32 s66, v254, 24
	v_readlane_b32 s67, v254, 25
	v_pk_fma_f32 v[36:37], v[82:83], v[26:27], v[36:37]
	v_pk_fma_f32 v[28:29], v[84:85], v[28:29], v[38:39]
	v_pk_fma_f32 v[30:31], v[86:87], v[30:31], v[40:41]
	v_mul_f32_e32 v33, v29, v29
	v_fmac_f32_e32 v33, v28, v28
	v_fmac_f32_e32 v33, v30, v30
	v_pk_fma_f32 v[26:27], v[80:81], v[24:25], v[34:35]
	v_fmac_f32_e32 v33, v31, v31
	v_lshlrev_b64 v[34:35], 1, v[42:43]
	v_fmac_f32_e32 v33, v26, v26
	v_cvt_pk_bf16_f32 v24, v28, v29
	v_lshl_add_u64 v[28:29], s[68:69], 0, v[34:35]
	v_fmac_f32_e32 v33, v27, v27
	v_cvt_pk_bf16_f32 v25, v30, v31
	v_cvt_pk_bf16_f32 v26, v26, v27
	v_cvt_pk_bf16_f32 v27, v36, v37
	global_store_dwordx4 v[28:29], v[24:27], off
	s_waitcnt vmcnt(10)
	s_nop 1
	v_mov_b32_e32 v24, v178
	v_mov_b32_e32 v25, v179
	v_mov_b32_e32 v26, v180
	v_mov_b32_e32 v27, v181
	s_nop 0
	v_mov_b32_e32 v28, v182
	v_mov_b32_e32 v29, v183
	v_mov_b32_e32 v30, v184
	v_mov_b32_e32 v31, v185
	v_fmac_f32_e32 v33, v36, v36
	v_fmac_f32_e32 v33, v37, v37
	v_pk_mul_f32 v[20:21], v[20:21], v[32:33] op_sel_hi:[1,0]
	v_pk_mul_f32 v[18:19], v[18:19], v[32:33] op_sel_hi:[1,0]
	v_pk_mul_f32 v[16:17], v[16:17], v[32:33] op_sel_hi:[1,0]
	v_pk_mul_f32 v[22:23], v[22:23], v[32:33] op_sel_hi:[1,0]
	v_or_b32_e32 v34, 0x100, v34
	v_pk_fma_f32 v[26:27], v[66:67], v[18:19], v[26:27]
	v_pk_fma_f32 v[20:21], v[68:69], v[20:21], v[28:29]
	v_pk_fma_f32 v[18:19], v[64:65], v[16:17], v[24:25]
	v_mul_f32_e32 v16, v21, v21
	v_pk_fma_f32 v[22:23], v[70:71], v[22:23], v[30:31]
	v_fmac_f32_e32 v16, v20, v20
	v_fmac_f32_e32 v16, v22, v22
	v_fmac_f32_e32 v16, v23, v23
	v_fmac_f32_e32 v16, v18, v18
	v_fmac_f32_e32 v16, v19, v19
	v_fmac_f32_e32 v16, v26, v26
	v_fmac_f32_e32 v16, v27, v27
	v_add_f32_e32 v24, v33, v16
	v_cvt_pk_bf16_f32 v16, v20, v21
	v_lshl_add_u64 v[20:21], s[68:69], 0, v[34:35]
	v_cvt_pk_bf16_f32 v17, v22, v23
	v_cvt_pk_bf16_f32 v18, v18, v19
	v_cvt_pk_bf16_f32 v19, v26, v27
	global_store_dwordx4 v[20:21], v[16:19], off
	ds_bpermute_b32 v16, v153, v24
	s_waitcnt lgkmcnt(0)
	v_add_f32_e32 v16, v24, v16
	ds_bpermute_b32 v17, v155, v16
	s_and_saveexec_b64 s[22:23], s[36:37]
	s_cbranch_execz .LBB0_698
	s_waitcnt lgkmcnt(0)
	v_add_f32_e32 v16, v16, v17
	ds_write_b32 v154, v16 offset:640
; DI unsigned cvt_pk_bf16(float lo, float hi) { unsigned r; asm volatile("v_cvt_pk_bf16_f32 %0, %1, %2" : "=v"(r) : "v"(lo), "v"(hi)); return r; }
; DI float bf_lo(unsigned w) { return __uint_as_float(w << 16); }
; DI float bf_hi(unsigned w) { return __uint_as_float(w & 0xffff0000u); }
;   DI void fused(f32x4 (&acc)[2][2][4][2], const Unit& u, int wr, int wc, int, int, LAS unsigned char* lds, int tid_) const {
;     ...
; #pragma unroll
;     for (int ai = 0; ai < 2; ++ai) {
; #pragma unroll
;       for (int m = 0; m < 4; ++m) { const int rl = ai * HALF + m * 16 + rl0; const float r1 = rs[rl]; float ss = 0.f;
; #pragma unroll
;         for (int bj = 0; bj < 2; ++bj) { const size_t o = (size_t)(u.pm * BM + rl) * 2048 + col0 + bj * HALF;
;           f32x4 xa, xc;
;           if constexpr (XF32) { xa = *(const f32x4*)(xin32 + o); xc = *(const f32x4*)(xin32 + o + 4); }
;           else { const u32x4 w = xw[ai][m][bj]; xa = (f32x4){bf_lo(w.x), bf_hi(w.x), bf_lo(w.y), bf_hi(w.y)}; xc = (f32x4){bf_lo(w.z), bf_hi(w.z), bf_lo(w.w), bf_hi(w.w)}; }
;           const f32x4 t0 = xa + acc[ai][bj][m][0] * r1 * g0[bj], t1 = xc + acc[ai][bj][m][1] * r1 * g1[bj];
;           ss += t0[0] * t0[0] + t0[1] * t0[1] + t0[2] * t0[2] + t0[3] * t0[3] + t1[0] * t1[0] + t1[1] * t1[1] + t1[2] * t1[2] + t1[3] * t1[3];
;           if (xout32) { *(f32x4*)(xout32 + o) = t0; *(f32x4*)(xout32 + o + 4) = t1; }
;           else { u32x4 w; w.x = cvt_pk_bf16(t0[0], t0[1]); w.y = cvt_pk_bf16(t0[2], t0[3]); w.z = cvt_pk_bf16(t1[0], t1[1]); w.w = cvt_pk_bf16(t1[2], t1[3]); *(u32x4*)(xb + o) = w; } }
;         if (!xout32) { ss += __shfl_xor(ss, 16); ss += __shfl_xor(ss, 32); if (fq == 0) part[wc * 256 + rl] = ss; } }
.LBB0_698:
	s_or_b64 exec, exec, s[22:23]
	v_add_u32_e32 v16, 0xb0, v148
	s_waitcnt lgkmcnt(0)
	v_ashrrev_i32_e32 v17, 31, v16
	v_lshlrev_b64 v[16:17], 11, v[16:17]
	v_readlane_b32 s52, v254, 10
	v_lshl_add_u64 v[26:27], v[16:17], 0, v[146:147]
	v_readlane_b32 s53, v254, 11
	ds_read_b32 v24, v156 offset:4800
	v_readlane_b32 s54, v254, 12
	v_lshl_add_u64 v[28:29], v[26:27], 2, s[52:53]
	s_waitcnt vmcnt(8)
	s_nop 1
	v_mov_b32_e32 v16, v186
	v_mov_b32_e32 v17, v187
	v_mov_b32_e32 v18, v188
	v_mov_b32_e32 v19, v189
	v_mov_b32_e32 v20, v190
	v_mov_b32_e32 v21, v191
	v_mov_b32_e32 v22, v192
	v_mov_b32_e32 v23, v193
	v_readlane_b32 s55, v254, 13
	s_waitcnt lgkmcnt(0)
	v_pk_mul_f32 v[12:13], v[12:13], v[24:25] op_sel_hi:[1,0]
	v_pk_mul_f32 v[14:15], v[14:15], v[24:25] op_sel_hi:[1,0]
	v_pk_mul_f32 v[10:11], v[10:11], v[24:25] op_sel_hi:[1,0]
	v_pk_mul_f32 v[8:9], v[8:9], v[24:25] op_sel_hi:[1,0]
	v_pk_mul_f32 v[4:5], v[4:5], v[24:25] op_sel_hi:[1,0]
	v_pk_mul_f32 v[2:3], v[2:3], v[24:25] op_sel_hi:[1,0]
	v_pk_mul_f32 v[0:1], v[0:1], v[24:25] op_sel_hi:[1,0]
	v_pk_mul_f32 v[6:7], v[6:7], v[24:25] op_sel_hi:[1,0]
	v_readlane_b32 s56, v254, 14
	v_readlane_b32 s57, v254, 15
	v_readlane_b32 s58, v254, 16
	v_readlane_b32 s59, v254, 17
	v_readlane_b32 s60, v254, 18
	v_readlane_b32 s61, v254, 19
	v_readlane_b32 s62, v254, 20
	v_readlane_b32 s63, v254, 21
	v_readlane_b32 s64, v254, 22
	v_readlane_b32 s65, v254, 23
	v_readlane_b32 s66, v254, 24
	v_readlane_b32 s67, v254, 25
	v_pk_fma_f32 v[18:19], v[82:83], v[10:11], v[18:19]
	v_pk_fma_f32 v[12:13], v[84:85], v[12:13], v[20:21]
	v_pk_fma_f32 v[14:15], v[86:87], v[14:15], v[22:23]
	v_mul_f32_e32 v20, v13, v13
	v_fmac_f32_e32 v20, v12, v12
	v_fmac_f32_e32 v20, v14, v14
	v_pk_fma_f32 v[10:11], v[80:81], v[8:9], v[16:17]
	v_fmac_f32_e32 v20, v15, v15
	v_lshlrev_b64 v[16:17], 1, v[26:27]
	v_fmac_f32_e32 v20, v10, v10
	v_cvt_pk_bf16_f32 v8, v12, v13
	v_lshl_add_u64 v[12:13], s[68:69], 0, v[16:17]
	v_fmac_f32_e32 v20, v11, v11
	v_cvt_pk_bf16_f32 v9, v14, v15
	v_cvt_pk_bf16_f32 v10, v10, v11
	v_cvt_pk_bf16_f32 v11, v18, v19
	global_store_dwordx4 v[12:13], v[8:11], off
	s_waitcnt vmcnt(6)
	s_nop 1
	v_mov_b32_e32 v8, v194
	v_mov_b32_e32 v9, v195
	v_mov_b32_e32 v10, v196
	v_mov_b32_e32 v11, v197
	s_nop 0
	v_mov_b32_e32 v12, v198
	v_mov_b32_e32 v13, v199
	v_mov_b32_e32 v14, v200
	v_mov_b32_e32 v15, v201
	v_fmac_f32_e32 v20, v18, v18
	v_fmac_f32_e32 v20, v19, v19
	v_or_b32_e32 v16, 0x100, v16
	v_pk_fma_f32 v[10:11], v[66:67], v[2:3], v[10:11]
	v_pk_fma_f32 v[4:5], v[68:69], v[4:5], v[12:13]
	v_pk_fma_f32 v[2:3], v[64:65], v[0:1], v[8:9]
	v_mul_f32_e32 v0, v5, v5
	v_pk_fma_f32 v[6:7], v[70:71], v[6:7], v[14:15]
	v_fmac_f32_e32 v0, v4, v4
	v_fmac_f32_e32 v0, v6, v6
	v_fmac_f32_e32 v0, v7, v7
	v_fmac_f32_e32 v0, v2, v2
	v_fmac_f32_e32 v0, v3, v3
	v_fmac_f32_e32 v0, v10, v10
	v_fmac_f32_e32 v0, v11, v11
	v_add_f32_e32 v8, v20, v0
	v_cvt_pk_bf16_f32 v0, v4, v5
	v_lshl_add_u64 v[4:5], s[68:69], 0, v[16:17]
	v_cvt_pk_bf16_f32 v1, v6, v7
	v_cvt_pk_bf16_f32 v2, v2, v3
	v_cvt_pk_bf16_f32 v3, v10, v11
	global_store_dwordx4 v[4:5], v[0:3], off
	ds_bpermute_b32 v0, v153, v8
	s_waitcnt lgkmcnt(0)
	v_add_f32_e32 v0, v8, v0
	ds_bpermute_b32 v1, v155, v0
	s_and_saveexec_b64 s[22:23], s[36:37]
	s_cbranch_execz .LBB0_700
	s_waitcnt lgkmcnt(0)
	v_add_f32_e32 v0, v0, v1
	ds_write_b32 v154, v0 offset:704
